# P6 k_pe rope pass software-pipelined: each iteration's 12 loads issued one iteration ahead into a landing register set (3 of 4 load round trips hidden)
# speedup vs baseline: 1.0055x; 1.0028x over previous
; template <int NR> DI void kpe_rows(const bf16* PS, const int* positions, bf16* KB, int m0, int mstride, int lane) {
;     const int hh = lane >> 3, part = lane & 7, jb = (4 * part) & 15;
;     u32x2 a1[NR], a2[NR]; int pos[NR];
; #pragma unroll
;     for (int r = 0; r < NR; ++r) { const size_t m = (size_t)(m0 + r * mstride); a1[r] = *(const u32x2*)(PS + m * 1024 + 896 + jb); a2[r] = *(const u32x2*)(PS + m * 1024 + 912 + jb); pos[r] = positions[m]; }
.LBB0_688:
	s_cmp_lt_i32 s66, 7
	s_cselect_b64 s[2:3], -1, 0
	s_add_u32 s6, s64, 0x11aec000
	s_addc_u32 s7, s65, 0
	s_and_b64 s[8:9], s[2:3], s[0:1]
	s_andn2_b64 vcc, exec, s[8:9]
	s_cbranch_vccnz .LBB0_764
	v_readlane_b32 s36, v253, 3
	s_cmpk_gt_i32 s58, 0x7fff
	v_readlane_b32 s38, v253, 5
	v_readlane_b32 s39, v253, 6
	v_readlane_b32 s37, v253, 4
	v_readlane_b32 s40, v253, 7
	v_readlane_b32 s41, v253, 8
	v_readlane_b32 s42, v253, 9
	v_readlane_b32 s43, v253, 10
	v_readlane_b32 s44, v253, 11
	v_readlane_b32 s45, v253, 12
	v_readlane_b32 s46, v253, 13
	v_readlane_b32 s47, v253, 14
	v_readlane_b32 s48, v253, 15
	v_readlane_b32 s49, v253, 16
	v_readlane_b32 s50, v253, 17
	v_readlane_b32 s51, v253, 18
	s_cbranch_scc1 .LBB0_692
	v_lshlrev_b32_e32 v0, 2, v197
	v_and_b32_e32 v10, 12, v0
	s_waitcnt lgkmcnt(0)
	v_mov_b32_e32 v1, 0x3f50624d
	v_mov_b32_e32 v2, 0x3f847ae1
	v_cmp_eq_u32_e32 vcc, 8, v10
	v_mov_b32_e32 v3, 0x47ae147b
	v_lshrrev_b32_e32 v0, 3, v196
	v_cndmask_b32_e32 v1, v1, v2, vcc
	v_mov_b32_e32 v2, 0xd2f1a9fc
	v_cndmask_b32_e32 v2, v2, v3, vcc
	v_mov_b32_e32 v3, 0x9999999a
	v_cmp_ne_u32_e32 vcc, 4, v10
	v_mul_u32_u24_e32 v0, 0x60, v0
	v_readlane_b32 s0, v253, 51
	v_cndmask_b32_e32 v2, v3, v2, vcc
	v_mov_b32_e32 v3, 0x3fb99999
	v_cndmask_b32_e32 v3, v3, v1, vcc
	v_lshlrev_b32_e32 v0, 1, v0
	v_mov_b32_e32 v1, 0
	v_readlane_b32 s1, v253, 52
	v_and_b32_e32 v14, 7, v197
	s_ashr_i32 s69, s68, 31
	v_lshl_add_u64 v[12:13], s[0:1], 0, v[0:1]
	v_mov_b32_e32 v0, 0x3ff00000
	v_cmp_ne_u32_e64 s[0:1], 0, v10
	s_mov_b32 s2, 0x6dc9c883
	v_cmp_gt_u32_e32 vcc, 4, v14
	v_cndmask_b32_e64 v3, v0, v3, s[0:1]
	v_cndmask_b32_e64 v2, 0, v2, s[0:1]
	s_mov_b32 s0, 0x3c1c381e
	s_mov_b32 s1, 0x3fe1feb3
	v_mul_f64 v[4:5], v[2:3], s[0:1]
	s_mov_b32 s0, 0x6248490f
	s_mov_b32 s1, 0x3fd43d13
	v_mul_f64 v[6:7], v[2:3], s[0:1]
	s_mov_b32 s0, 0xe3769f3f
	v_lshlrev_b32_e32 v0, 1, v10
	s_mov_b32 s1, 0x3fc6c310
	v_lshl_add_u64 v[10:11], s[76:77], 0, v[0:1]
	v_lshlrev_b32_e32 v0, 3, v14
	v_mul_f64 v[8:9], v[2:3], s[0:1]
	v_lshl_add_u64 v[12:13], v[12:13], 0, v[0:1]
	s_lshl_b32 s14, s70, 4
	s_mul_i32 s15, s70, 24
	s_lshl_b64 s[0:1], s[68:69], 2
	s_mov_b32 s3, 0x3fc45f30
	v_mov_b32_e32 v0, 0x600
	s_mov_b32 s4, s58
	s_mov_b32 s98, s4
	s_min_i32 s100, s98, 0x7fff
	s_mov_b32 s101, 0
	s_lshl_b64 s[100:101], s[100:101], 11
	v_lshl_add_u64 v[224:225], v[10:11], 0, s[100:101]
	global_load_dwordx2 v[200:201], v[224:225], off offset:1792
	global_load_dwordx2 v[202:203], v[224:225], off offset:1824
	s_min_i32 s100, s98, 0x7fff
	s_lshl_b32 s100, s100, 2
	s_add_u32 s100, s38, s100
	s_addc_u32 s101, s39, 0
	global_load_dword v204, v1, s[100:101]
	s_add_i32 s98, s98, s68
	s_min_i32 s100, s98, 0x7fff
	s_mov_b32 s101, 0
	s_lshl_b64 s[100:101], s[100:101], 11
	v_lshl_add_u64 v[224:225], v[10:11], 0, s[100:101]
	global_load_dwordx2 v[206:207], v[224:225], off offset:1792
	global_load_dwordx2 v[208:209], v[224:225], off offset:1824
	s_min_i32 s100, s98, 0x7fff
	s_lshl_b32 s100, s100, 2
	s_add_u32 s100, s38, s100
	s_addc_u32 s101, s39, 0
	global_load_dword v210, v1, s[100:101]
	s_add_i32 s98, s98, s68
	s_min_i32 s100, s98, 0x7fff
	s_mov_b32 s101, 0
	s_lshl_b64 s[100:101], s[100:101], 11
	v_lshl_add_u64 v[224:225], v[10:11], 0, s[100:101]
	global_load_dwordx2 v[212:213], v[224:225], off offset:1792
	global_load_dwordx2 v[214:215], v[224:225], off offset:1824
	s_min_i32 s100, s98, 0x7fff
	s_lshl_b32 s100, s100, 2
	s_add_u32 s100, s38, s100
	s_addc_u32 s101, s39, 0
	global_load_dword v216, v1, s[100:101]
	s_add_i32 s98, s98, s68
	s_min_i32 s100, s98, 0x7fff
	s_mov_b32 s101, 0
	s_lshl_b64 s[100:101], s[100:101], 11
	v_lshl_add_u64 v[224:225], v[10:11], 0, s[100:101]
	global_load_dwordx2 v[218:219], v[224:225], off offset:1792
	global_load_dwordx2 v[220:221], v[224:225], off offset:1824
	s_min_i32 s100, s98, 0x7fff
	s_lshl_b32 s100, s100, 2
	s_add_u32 s100, s38, s100
	s_addc_u32 s101, s39, 0
	global_load_dword v222, v1, s[100:101]
	s_waitcnt vmcnt(0)
.LBB0_691:
	s_ashr_i32 s5, s4, 31
	s_lshl_b64 s[10:11], s[4:5], 11
	v_lshl_add_u64 v[14:15], v[10:11], 0, s[10:11]
	s_lshl_b64 s[10:11], s[4:5], 2
	s_add_u32 s16, s38, s10
	s_addc_u32 s17, s39, s11
	s_nop 0
	s_add_i32 s10, s4, s68
	s_ashr_i32 s11, s10, 31
	s_lshl_b64 s[12:13], s[10:11], 11
	s_add_u32 s16, s16, s0
	s_addc_u32 s17, s17, s1
	v_lshl_add_u64 v[20:21], v[10:11], 0, s[12:13]
	s_nop 0
	s_add_i32 s12, s14, s4
	v_mad_i64_i32 v[18:19], s[16:17], s4, v0, v[12:13]
	s_ashr_i32 s13, s12, 31
	s_add_i32 s11, s10, s68
	s_lshl_b64 s[16:17], s[12:13], 11
	s_lshl_b64 s[18:19], s[12:13], 2
	v_lshl_add_u64 v[24:25], v[10:11], 0, s[16:17]
	s_add_u32 s16, s38, s18
	s_addc_u32 s17, s39, s19
	s_add_i32 s4, s15, s4
	s_ashr_i32 s5, s4, 31
	s_add_i32 s11, s11, s68
	s_lshl_b64 s[18:19], s[4:5], 11
	s_lshl_b64 s[20:21], s[4:5], 2
	v_lshl_add_u64 v[26:27], v[10:11], 0, s[18:19]
	s_add_u32 s18, s38, s20
	s_nop 0
	s_nop 0
	s_nop 0
	s_addc_u32 s19, s39, s21
	s_waitcnt vmcnt(4)
	v_mov_b64_e32 v[16:17], v[200:201]
	v_mov_b64_e32 v[14:15], v[202:203]
	v_mov_b32_e32 v36, v204
	v_mov_b64_e32 v[22:23], v[206:207]
	v_mov_b64_e32 v[20:21], v[208:209]
	v_mov_b32_e32 v52, v210
	v_mov_b64_e32 v[28:29], v[212:213]
	v_mov_b64_e32 v[24:25], v[214:215]
	v_mov_b32_e32 v53, v216
	v_mov_b64_e32 v[30:31], v[218:219]
	v_mov_b64_e32 v[26:27], v[220:221]
	v_mov_b32_e32 v54, v222
	s_add_i32 s98, s11, s68
	s_cmpk_gt_i32 s98, 0x7fff
	s_cbranch_scc1 .Lkpe_skip
; DI unsigned pk2(float lo, float hi) { f32x2_t v = {lo, hi}; bf16x2_t b = __builtin_convertvector(v, bf16x2_t); return __builtin_bit_cast(unsigned, b); }
; DI float bflo(unsigned u) { return __uint_as_float(u << 16); }
; DI float bfhi(unsigned u) { return __uint_as_float(u & 0xffff0000u); }
; DI void rope_cs(int pos, int j, float& c, float& s) {
;     const int jl = j & 3, jh = j >> 2;
;     const double fb = jl == 0 ? 1.0 : jl == 1 ? 0.5623413251903491 : jl == 2 ? 0.31622776601683794 : 0.1778279410038923;
;     const double fs = jh == 0 ? 1.0 : jh == 1 ? 0.1 : jh == 2 ? 0.01 : 0.001;
;     double a = (double)pos * (fb * fs) * 0.15915494309189535;
;     a -= __builtin_rint(a);
;     const float fr = (float)a;
;     c = __builtin_amdgcn_cosf(fr); s = __builtin_amdgcn_sinf(fr);
; }
; template <int NR> DI void kpe_rows(const bf16* PS, const int* positions, bf16* KB, int m0, int mstride, int lane) {
;     ...
;     for (int r = 0; r < NR; ++r) { const size_t m = (size_t)(m0 + r * mstride); a1[r] = *(const u32x2*)(PS + m * 1024 + 896 + jb); a2[r] = *(const u32x2*)(PS + m * 1024 + 912 + jb); pos[r] = positions[m]; }
; #pragma unroll
;     for (int r = 0; r < NR; ++r) { const size_t m = (size_t)(m0 + r * mstride);
;         const float x1[4] = {bflo(a1[r].x), bfhi(a1[r].x), bflo(a1[r].y), bfhi(a1[r].y)}, x2[4] = {bflo(a2[r].x), bfhi(a2[r].x), bflo(a2[r].y), bfhi(a2[r].y)};
;         float o[4];
; #pragma unroll
;         for (int i = 0; i < 4; ++i) { float c, s; rope_cs(pos[r], jb + i, c, s); o[i] = part < 4 ? x1[i] * c - x2[i] * s : x1[i] * s + x2[i] * c; }
;         u32x2 w; w.x = pk2(o[0], o[1]); w.y = pk2(o[2], o[3]);
;         *(u32x2*)(KB + m * 768 + hh * 96 + 64 + 4 * part) = w; }
	s_min_i32 s100, s98, 0x7fff
	s_mov_b32 s101, 0
	s_lshl_b64 s[100:101], s[100:101], 11
	v_lshl_add_u64 v[224:225], v[10:11], 0, s[100:101]
	global_load_dwordx2 v[200:201], v[224:225], off offset:1792
	global_load_dwordx2 v[202:203], v[224:225], off offset:1824
	s_min_i32 s100, s98, 0x7fff
	s_lshl_b32 s100, s100, 2
	s_add_u32 s100, s38, s100
	s_addc_u32 s101, s39, 0
	global_load_dword v204, v1, s[100:101]
	s_add_i32 s98, s98, s68
	s_min_i32 s100, s98, 0x7fff
	s_mov_b32 s101, 0
	s_lshl_b64 s[100:101], s[100:101], 11
	v_lshl_add_u64 v[224:225], v[10:11], 0, s[100:101]
	global_load_dwordx2 v[206:207], v[224:225], off offset:1792
	global_load_dwordx2 v[208:209], v[224:225], off offset:1824
	s_min_i32 s100, s98, 0x7fff
	s_lshl_b32 s100, s100, 2
	s_add_u32 s100, s38, s100
	s_addc_u32 s101, s39, 0
	global_load_dword v210, v1, s[100:101]
	s_add_i32 s98, s98, s68
	s_min_i32 s100, s98, 0x7fff
	s_mov_b32 s101, 0
	s_lshl_b64 s[100:101], s[100:101], 11
	v_lshl_add_u64 v[224:225], v[10:11], 0, s[100:101]
	global_load_dwordx2 v[212:213], v[224:225], off offset:1792
	global_load_dwordx2 v[214:215], v[224:225], off offset:1824
	s_min_i32 s100, s98, 0x7fff
	s_lshl_b32 s100, s100, 2
	s_add_u32 s100, s38, s100
	s_addc_u32 s101, s39, 0
	global_load_dword v216, v1, s[100:101]
	s_add_i32 s98, s98, s68
	s_min_i32 s100, s98, 0x7fff
	s_mov_b32 s101, 0
	s_lshl_b64 s[100:101], s[100:101], 11
	v_lshl_add_u64 v[224:225], v[10:11], 0, s[100:101]
	global_load_dwordx2 v[218:219], v[224:225], off offset:1792
	global_load_dwordx2 v[220:221], v[224:225], off offset:1824
	s_min_i32 s100, s98, 0x7fff
	s_lshl_b32 s100, s100, 2
	s_add_u32 s100, s38, s100
	s_addc_u32 s101, s39, 0
	global_load_dword v222, v1, s[100:101]
.Lkpe_skip:
	v_lshlrev_b32_e32 v32, 16, v16
	v_lshlrev_b32_e32 v34, 16, v14
	v_and_b32_e32 v35, 0xffff0000, v14
	v_cvt_f64_i32_e32 v[36:37], v36
	v_mul_f64 v[38:39], v[2:3], v[36:37]
	v_mul_f64 v[40:41], v[4:5], v[36:37]
	v_mul_f64 v[42:43], v[6:7], v[36:37]
	v_mul_f64 v[36:37], v[8:9], v[36:37]
	v_mul_f64 v[44:45], v[38:39], s[2:3]
	v_mul_f64 v[46:47], v[40:41], s[2:3]
	v_mul_f64 v[48:49], v[42:43], s[2:3]
	v_mul_f64 v[50:51], v[36:37], s[2:3]
	v_rndne_f64_e32 v[44:45], v[44:45]
	v_rndne_f64_e32 v[46:47], v[46:47]
	v_rndne_f64_e32 v[48:49], v[48:49]
	v_rndne_f64_e32 v[50:51], v[50:51]
	v_fma_f64 v[38:39], v[38:39], s[2:3], -v[44:45]
	v_fma_f64 v[40:41], v[40:41], s[2:3], -v[46:47]
	v_fma_f64 v[42:43], v[42:43], s[2:3], -v[48:49]
	v_fma_f64 v[36:37], v[36:37], s[2:3], -v[50:51]
	v_cvt_f32_f64_e32 v39, v[38:39]
	v_cvt_f32_f64_e32 v41, v[40:41]
	v_cvt_f32_f64_e32 v43, v[42:43]
	v_cvt_f32_f64_e32 v47, v[36:37]
	v_cvt_f64_i32_e32 v[44:45], v52
	v_cos_f32_e32 v38, v39
	v_sin_f32_e32 v40, v39
	v_cos_f32_e32 v39, v41
	v_sin_f32_e32 v41, v41
	v_cos_f32_e32 v42, v43
	v_sin_f32_e32 v46, v43
	v_cos_f32_e32 v43, v47
	v_sin_f32_e32 v47, v47
	v_mul_f64 v[36:37], v[2:3], v[44:45]
	v_mul_f64 v[48:49], v[36:37], s[2:3]
	v_lshlrev_b32_e32 v14, 16, v15
	v_and_b32_e32 v15, 0xffff0000, v15
	v_rndne_f64_e32 v[48:49], v[48:49]
	v_and_b32_e32 v33, 0xffff0000, v16
	v_lshlrev_b32_e32 v16, 16, v17
	v_and_b32_e32 v17, 0xffff0000, v17
	v_fma_f64 v[36:37], v[36:37], s[2:3], -v[48:49]
	v_pk_mul_f32 v[48:49], v[40:41], v[34:35]
	v_pk_mul_f32 v[34:35], v[38:39], v[34:35]
	v_pk_mul_f32 v[50:51], v[46:47], v[14:15]
	v_pk_mul_f32 v[14:15], v[42:43], v[14:15]
	v_pk_fma_f32 v[38:39], v[38:39], v[32:33], v[48:49] neg_lo:[0,0,1] neg_hi:[0,0,1]
	v_pk_fma_f32 v[32:33], v[40:41], v[32:33], v[34:35]
	v_pk_fma_f32 v[34:35], v[42:43], v[16:17], v[50:51] neg_lo:[0,0,1] neg_hi:[0,0,1]
	v_pk_fma_f32 v[14:15], v[46:47], v[16:17], v[14:15]
	v_cndmask_b32_e32 v16, v33, v39, vcc
	v_cndmask_b32_e32 v17, v32, v38, vcc
	v_cndmask_b32_e32 v15, v15, v35, vcc
	v_cndmask_b32_e32 v32, v14, v34, vcc
	v_cvt_pk_bf16_f32 v14, v17, v16
	v_cvt_pk_bf16_f32 v15, v32, v15
	global_store_dwordx2 v[18:19], v[14:15], off offset:128
	v_mul_f64 v[18:19], v[4:5], v[44:45]
	v_mul_f64 v[32:33], v[18:19], s[2:3]
	v_rndne_f64_e32 v[32:33], v[32:33]
	v_fma_f64 v[18:19], v[18:19], s[2:3], -v[32:33]
	v_cvt_f32_f64_e32 v15, v[36:37]
	v_cvt_f32_f64_e32 v17, v[18:19]
	v_cos_f32_e32 v14, v15
	v_sin_f32_e32 v16, v15
	v_cos_f32_e32 v15, v17
	v_sin_f32_e32 v17, v17
	v_lshlrev_b32_e32 v32, 16, v20
	v_and_b32_e32 v33, 0xffff0000, v20
	v_lshlrev_b32_e32 v18, 16, v22
	v_and_b32_e32 v19, 0xffff0000, v22
	v_pk_mul_f32 v[34:35], v[16:17], v[32:33]
	v_lshlrev_b32_e32 v20, 16, v21
	v_pk_fma_f32 v[34:35], v[14:15], v[18:19], v[34:35] neg_lo:[0,0,1] neg_hi:[0,0,1]
	v_pk_mul_f32 v[14:15], v[14:15], v[32:33]
	v_and_b32_e32 v21, 0xffff0000, v21
	v_pk_fma_f32 v[14:15], v[16:17], v[18:19], v[14:15]
	v_mul_f64 v[18:19], v[8:9], v[44:45]
	v_cndmask_b32_e32 v35, v15, v35, vcc
	v_cndmask_b32_e32 v34, v14, v34, vcc
	v_mul_f64 v[14:15], v[6:7], v[44:45]
	v_mul_f64 v[16:17], v[14:15], s[2:3]
	v_mul_f64 v[32:33], v[18:19], s[2:3]
	v_rndne_f64_e32 v[16:17], v[16:17]
	v_rndne_f64_e32 v[32:33], v[32:33]
	v_fma_f64 v[14:15], v[14:15], s[2:3], -v[16:17]
; DI unsigned pk2(float lo, float hi) { f32x2_t v = {lo, hi}; bf16x2_t b = __builtin_convertvector(v, bf16x2_t); return __builtin_bit_cast(unsigned, b); }
; DI float bflo(unsigned u) { return __uint_as_float(u << 16); }
; DI float bfhi(unsigned u) { return __uint_as_float(u & 0xffff0000u); }
; DI void rope_cs(int pos, int j, float& c, float& s) {
;     const int jl = j & 3, jh = j >> 2;
;     const double fb = jl == 0 ? 1.0 : jl == 1 ? 0.5623413251903491 : jl == 2 ? 0.31622776601683794 : 0.1778279410038923;
;     const double fs = jh == 0 ? 1.0 : jh == 1 ? 0.1 : jh == 2 ? 0.01 : 0.001;
;     double a = (double)pos * (fb * fs) * 0.15915494309189535;
;     a -= __builtin_rint(a);
;     const float fr = (float)a;
;     c = __builtin_amdgcn_cosf(fr); s = __builtin_amdgcn_sinf(fr);
; }
; template <int NR> DI void kpe_rows(const bf16* PS, const int* positions, bf16* KB, int m0, int mstride, int lane) {
;     ...
;     for (int r = 0; r < NR; ++r) { const size_t m = (size_t)(m0 + r * mstride);
;         const float x1[4] = {bflo(a1[r].x), bfhi(a1[r].x), bflo(a1[r].y), bfhi(a1[r].y)}, x2[4] = {bflo(a2[r].x), bfhi(a2[r].x), bflo(a2[r].y), bfhi(a2[r].y)};
;         float o[4];
; #pragma unroll
;         for (int i = 0; i < 4; ++i) { float c, s; rope_cs(pos[r], jb + i, c, s); o[i] = part < 4 ? x1[i] * c - x2[i] * s : x1[i] * s + x2[i] * c; }
;         u32x2 w; w.x = pk2(o[0], o[1]); w.y = pk2(o[2], o[3]);
;         *(u32x2*)(KB + m * 768 + hh * 96 + 64 + 4 * part) = w; }
	v_fma_f64 v[18:19], v[18:19], s[2:3], -v[32:33]
	v_cvt_f32_f64_e32 v15, v[14:15]
	v_cvt_f32_f64_e32 v17, v[18:19]
	v_cos_f32_e32 v14, v15
	v_sin_f32_e32 v16, v15
	v_cos_f32_e32 v15, v17
	v_sin_f32_e32 v17, v17
	v_lshlrev_b32_e32 v18, 16, v23
	v_and_b32_e32 v19, 0xffff0000, v23
	v_pk_mul_f32 v[22:23], v[16:17], v[20:21]
	s_nop 0
	v_pk_fma_f32 v[22:23], v[14:15], v[18:19], v[22:23] neg_lo:[0,0,1] neg_hi:[0,0,1]
	v_pk_mul_f32 v[14:15], v[14:15], v[20:21]
	s_nop 0
	v_pk_fma_f32 v[14:15], v[16:17], v[18:19], v[14:15]
	s_nop 0
	v_cndmask_b32_e32 v15, v15, v23, vcc
	v_cndmask_b32_e32 v16, v14, v22, vcc
	v_cvt_pk_bf16_f32 v14, v34, v35
	v_cvt_pk_bf16_f32 v15, v16, v15
	v_mad_i64_i32 v[16:17], s[16:17], s10, v0, v[12:13]
	global_store_dwordx2 v[16:17], v[14:15], off offset:128
	v_cvt_f64_i32_e32 v[14:15], v53
	v_mul_f64 v[16:17], v[2:3], v[14:15]
	v_mul_f64 v[20:21], v[4:5], v[14:15]
	v_mul_f64 v[18:19], v[16:17], s[2:3]
	v_mul_f64 v[22:23], v[20:21], s[2:3]
	v_rndne_f64_e32 v[18:19], v[18:19]
	v_rndne_f64_e32 v[22:23], v[22:23]
	v_fma_f64 v[16:17], v[16:17], s[2:3], -v[18:19]
	v_fma_f64 v[20:21], v[20:21], s[2:3], -v[22:23]
	v_cvt_f32_f64_e32 v17, v[16:17]
	v_cvt_f32_f64_e32 v19, v[20:21]
	v_cos_f32_e32 v16, v17
	v_sin_f32_e32 v18, v17
	v_cos_f32_e32 v17, v19
	v_sin_f32_e32 v19, v19
	v_lshlrev_b32_e32 v22, 16, v24
	v_and_b32_e32 v23, 0xffff0000, v24
	v_lshlrev_b32_e32 v20, 16, v28
	v_and_b32_e32 v21, 0xffff0000, v28
	v_pk_mul_f32 v[32:33], v[18:19], v[22:23]
	s_nop 0
	v_pk_fma_f32 v[32:33], v[16:17], v[20:21], v[32:33] neg_lo:[0,0,1] neg_hi:[0,0,1]
	v_pk_mul_f32 v[16:17], v[16:17], v[22:23]
	s_nop 0
	v_pk_fma_f32 v[16:17], v[18:19], v[20:21], v[16:17]
	s_nop 0
	v_cndmask_b32_e32 v24, v17, v33, vcc
	v_cndmask_b32_e32 v28, v16, v32, vcc
	v_mul_f64 v[16:17], v[6:7], v[14:15]
	v_mul_f64 v[14:15], v[8:9], v[14:15]
	v_mul_f64 v[18:19], v[16:17], s[2:3]
	v_mul_f64 v[20:21], v[14:15], s[2:3]
	v_rndne_f64_e32 v[18:19], v[18:19]
	v_rndne_f64_e32 v[20:21], v[20:21]
	v_fma_f64 v[16:17], v[16:17], s[2:3], -v[18:19]
	v_fma_f64 v[14:15], v[14:15], s[2:3], -v[20:21]
	v_cvt_f32_f64_e32 v17, v[16:17]
	v_cvt_f32_f64_e32 v14, v[14:15]
	v_sin_f32_e32 v18, v17
	v_sin_f32_e32 v19, v14
	v_cos_f32_e32 v16, v17
	v_cos_f32_e32 v17, v14
	v_lshlrev_b32_e32 v20, 16, v25
	v_and_b32_e32 v21, 0xffff0000, v25
	v_lshlrev_b32_e32 v14, 16, v29
	v_and_b32_e32 v15, 0xffff0000, v29
	v_pk_mul_f32 v[22:23], v[18:19], v[20:21]
	s_nop 0
	v_pk_fma_f32 v[22:23], v[16:17], v[14:15], v[22:23] neg_lo:[0,0,1] neg_hi:[0,0,1]
	v_pk_mul_f32 v[16:17], v[16:17], v[20:21]
	s_nop 0
	v_pk_fma_f32 v[14:15], v[18:19], v[14:15], v[16:17]
	s_nop 0
	v_cndmask_b32_e32 v15, v15, v23, vcc
	v_cndmask_b32_e32 v16, v14, v22, vcc
	v_cvt_pk_bf16_f32 v14, v28, v24
	v_cvt_pk_bf16_f32 v15, v16, v15
	v_mad_i64_i32 v[16:17], s[12:13], s12, v0, v[12:13]
	global_store_dwordx2 v[16:17], v[14:15], off offset:128
	v_cvt_f64_i32_e32 v[14:15], v54
	v_mul_f64 v[16:17], v[2:3], v[14:15]
	v_mul_f64 v[20:21], v[4:5], v[14:15]
	v_mul_f64 v[18:19], v[16:17], s[2:3]
	v_mul_f64 v[22:23], v[20:21], s[2:3]
	v_rndne_f64_e32 v[18:19], v[18:19]
	v_rndne_f64_e32 v[22:23], v[22:23]
	v_fma_f64 v[16:17], v[16:17], s[2:3], -v[18:19]
	v_fma_f64 v[20:21], v[20:21], s[2:3], -v[22:23]
	v_cvt_f32_f64_e32 v17, v[16:17]
	v_cvt_f32_f64_e32 v19, v[20:21]
	v_cos_f32_e32 v16, v17
	v_sin_f32_e32 v18, v17
	v_cos_f32_e32 v17, v19
	v_sin_f32_e32 v19, v19
	v_lshlrev_b32_e32 v22, 16, v26
	v_and_b32_e32 v23, 0xffff0000, v26
	v_lshlrev_b32_e32 v20, 16, v30
	v_and_b32_e32 v21, 0xffff0000, v30
	v_pk_mul_f32 v[24:25], v[18:19], v[22:23]
	s_nop 0
	v_pk_fma_f32 v[24:25], v[16:17], v[20:21], v[24:25] neg_lo:[0,0,1] neg_hi:[0,0,1]
	v_pk_mul_f32 v[16:17], v[16:17], v[22:23]
	s_nop 0
	v_pk_fma_f32 v[16:17], v[18:19], v[20:21], v[16:17]
	s_nop 0
	v_cndmask_b32_e32 v25, v17, v25, vcc
	v_cndmask_b32_e32 v24, v16, v24, vcc
	v_mul_f64 v[16:17], v[6:7], v[14:15]
	v_mul_f64 v[14:15], v[8:9], v[14:15]
	v_mul_f64 v[18:19], v[16:17], s[2:3]
	v_mul_f64 v[20:21], v[14:15], s[2:3]
	v_rndne_f64_e32 v[18:19], v[18:19]
	v_rndne_f64_e32 v[20:21], v[20:21]
	v_fma_f64 v[16:17], v[16:17], s[2:3], -v[18:19]
	v_fma_f64 v[14:15], v[14:15], s[2:3], -v[20:21]
	v_cvt_f32_f64_e32 v17, v[16:17]
	v_cvt_f32_f64_e32 v14, v[14:15]
	v_sin_f32_e32 v18, v17
	v_sin_f32_e32 v19, v14
	v_cos_f32_e32 v16, v17
	v_cos_f32_e32 v17, v14
	v_lshlrev_b32_e32 v20, 16, v27
	v_and_b32_e32 v21, 0xffff0000, v27
	v_lshlrev_b32_e32 v14, 16, v31
	v_and_b32_e32 v15, 0xffff0000, v31
	v_pk_mul_f32 v[22:23], v[18:19], v[20:21]
	s_nop 0
	v_pk_fma_f32 v[22:23], v[16:17], v[14:15], v[22:23] neg_lo:[0,0,1] neg_hi:[0,0,1]
	v_pk_mul_f32 v[16:17], v[16:17], v[20:21]
	s_nop 0
	v_pk_fma_f32 v[14:15], v[18:19], v[14:15], v[16:17]
	s_nop 0
	v_cndmask_b32_e32 v15, v15, v23, vcc
	v_cndmask_b32_e32 v16, v14, v22, vcc
	v_cvt_pk_bf16_f32 v15, v16, v15
	v_mad_i64_i32 v[16:17], s[4:5], s4, v0, v[12:13]
	s_add_i32 s4, s11, s68
	v_cvt_pk_bf16_f32 v14, v24, v25
	s_cmpk_gt_i32 s4, 0x7fff
	global_store_dwordx2 v[16:17], v[14:15], off offset:128
	s_cbranch_scc0 .LBB0_691
